# NSA phase: waves 4-7 start 1024 cycles later so SIMD partners are out of phase
# speedup vs baseline: 1.0050x; 1.0033x over previous
; #define LAS __attribute__((address_space(3)))
; __device__ __forceinline__ const float* P_in(const Params&, int i) { return (const float*)karg_ld(8 * i); }
; #define LAUNDER(x) asm volatile("" : "+v"(x))
; __device__ __forceinline__ void nsa_unit(const Params& p, int bg, int jq, LAS unsigned char* lds, int wave, int lane, bool build_lut) {
;     LAUNDER(lane);
;     const unsigned char* ws = P_ws(p);
;     const bf16_t* qb = (const bf16_t*)(ws + WS_R1 + R_Q);
;     const bf16_t* kcmp = (const bf16_t*)(ws + WS_R1 + R_KCMP) + (size_t)bg * NCMP * 64;
;     const bf16_t* vcmpT = (const bf16_t*)(ws + WS_R1 + R_VCMPT) + (size_t)bg * NCMP * 64;
;     const unsigned char* ks8 = ws + WS_R1 + R_KS + (size_t)bg * S * 64;
;     const unsigned char* vs8 = ws + WS_R1 + R_VST + (size_t)bg * S * 64;
;     const bf16_t* kwb = (const bf16_t*)(ws + WS_R1 + R_KW) + (size_t)bg * S * 64;
;     const bf16_t* vwT = (const bf16_t*)(ws + WS_R1 + R_VWT) + (size_t)bg * S * 64;
;     const float* gates = (const float*)(ws + WS_R1 + R_GATES);
;     bf16_t* mixed = (bf16_t*)(ws + WS_AN);
;     const float* relb = P_in(p, 1);
;     const int b = bg >> 1, g = bg & 1;
;     LAS float* imp = (LAS float*)(lds + wave * NSA_WAVE_LDS);
;     LAS unsigned* selw = (LAS unsigned*)(lds + wave * NSA_WAVE_LDS + 8192);
;     LAS float* lut = (LAS float*)(lds + wave * NSA_WAVE_LDS + 8192 + 256);
;     LAS int* list = (LAS int*)(lds + wave * NSA_WAVE_LDS + 8192 + 256 + 2112);
;     const int c = lane & 31, h = lane >> 5, ql = c >> 2, r = c & 3;
;     const int tq0 = 64 * jq + 8 * wave, tq = tq0 + ql;
;     const size_t tok = (size_t)b * S + tq;
;     if (build_lut) {
;         for (int e = lane; e < 4 * 129; e += 64) {
;             const int rr = e / 129, n = e % 129;
;             int bk = n;
;             if (n >= 16) bk = 16 + (n >= 19) + (n >= 21) + (n >= 24) + (n >= 27) + (n >= 31) + (n >= 35) + (n >= 40) + (n >= 46) + (n >= 52) + (n >= 59) + (n >= 67) + (n >= 77) + (n >= 87) + (n >= 99) + (n >= 113);
;             lut[rr * 132 + n] = relb[bk * 8 + g * 4 + rr] * LOG2E;
;         }
; __global__ void __launch_bounds__(NTHREADS, 2) fwd_megakernel(Params p) {
;     ...
;                     for (int i = 0; i < 4; ++i) {
;                         const int jq = (i >> 1) * 128 + ((i & 1) ? (127 - j) : j);
;                         nsa_unit(p, bg, jq, lds, WAVE_F, LANE_F, i == 0);
.LBB0_1046:
	v_mov_b32_e32 v1, v222
	s_movk_i32 s6, 0xa8
	v_readfirstlane_b32 s4, v1
	s_ashr_i32 s12, s4, 6
	s_cmp_lg_u32 s27, 0
	s_cbranch_scc1 .Lno_stag
	s_cmp_lt_u32 s12, 4
	s_cbranch_scc1 .Lno_stag
	s_sleep 16
.Lno_stag:
	v_mov_b32_e32 v1, v222
	s_cmp_eq_u32 s27, 0
	s_waitcnt vmcnt(8)
	v_and_b32_e32 v145, 63, v1
	s_cselect_b64 s[4:5], -1, 0
	s_ashr_i32 s7, s6, 31
	s_add_u32 s6, s0, s6
	s_addc_u32 s7, s1, s7
	s_load_dwordx2 s[14:15], s[6:7], 0x0
	s_movk_i32 s7, 0x204
	v_cmp_gt_i32_e32 vcc, s7, v145
	s_mov_b32 s6, 8
	s_mul_i32 s18, s12, 0x4c00
	s_and_b64 s[8:9], s[4:5], vcc
	s_and_saveexec_b64 s[4:5], s[8:9]
	s_cbranch_execz .LBB0_1051
	s_ashr_i32 s7, s6, 31
	s_add_u32 s6, s0, s6
	s_addc_u32 s7, s1, s7
	s_load_dwordx2 s[6:7], s[6:7], 0x0
	s_add_i32 s8, s18, 0
	s_addk_i32 s8, 0x2100
	v_lshl_add_u32 v2, v145, 2, s8
	s_mov_b64 s[8:9], 0
	v_mov_b32_e32 v4, v145
	s_branch .LBB0_1049
